# scan inner loops rotated: one taken branch per 2 steps instead of two
# speedup vs baseline: 1.0060x; 1.0060x over previous
.LBB0_857:
	s_waitcnt lgkmcnt(11)
	ds_read_b128 v[22:25], v100
	s_waitcnt lgkmcnt(11)
	ds_read_b128 v[18:21], v100 offset:16
	s_waitcnt lgkmcnt(11)
	ds_read_b128 v[2:5], v100 offset:256
	s_waitcnt lgkmcnt(11)
	ds_read_b128 v[6:9], v100 offset:272
	s_waitcnt lgkmcnt(11)
	ds_read_b128 v[10:13], v100 offset:512
	s_waitcnt lgkmcnt(11)
	ds_read_b128 v[14:17], v100 offset:528
	s_waitcnt lgkmcnt(11)
	ds_read_b128 v[34:37], v100 offset:768
	s_waitcnt lgkmcnt(11)
	ds_read_b128 v[38:41], v100 offset:784
	s_waitcnt lgkmcnt(11)
	ds_read_b128 v[26:29], v100 offset:1024
	s_waitcnt lgkmcnt(11)
	ds_read_b128 v[30:33], v100 offset:1040
	s_waitcnt lgkmcnt(11)
	ds_read_b32 v94, v101 offset:1280
	s_waitcnt lgkmcnt(11)
	ds_read_b64 v[96:97], v1 offset:1536
	s_ashr_i32 s47, s46, 31
	s_lshl_b64 s[10:11], s[46:47], 9
	v_lshl_add_u64 v[92:93], v[82:83], 0, s[10:11]
	s_mov_b32 s7, 0
	s_mov_b32 s10, -2
	s_mov_b32 s46, 0
	v_readlane_b32 s2, v254, 61
	v_readlane_b32 s3, v254, 62
	s_branch .LBB0_859
.LBB0_859:
	s_waitcnt lgkmcnt(0)
	v_mov_b32_e32 v95, v96
	v_add_u32_e32 v96, s7, v100
	ds_read_b128 v[70:73], v96 offset:1568
	ds_read_b128 v[66:69], v96 offset:1584
	ds_read_b128 v[50:53], v96 offset:1824
	ds_read_b128 v[46:49], v96 offset:1840
	ds_read_b128 v[54:57], v96 offset:2080
	ds_read_b128 v[42:45], v96 offset:2096
	ds_read_b128 v[78:81], v96 offset:2336
	ds_read_b128 v[74:77], v96 offset:2352
	ds_read_b128 v[62:65], v96 offset:2592
	ds_read_b128 v[58:61], v96 offset:2608
	v_pk_fma_f32 v[34:35], v[84:85], v[34:35], 0 op_sel_hi:[1,1,0]
	v_pk_fma_f32 v[22:23], v[84:85], v[22:23], 0 op_sel_hi:[1,1,0]
	v_pk_fma_f32 v[34:35], v[86:87], v[36:37], v[34:35]
	v_pk_fma_f32 v[22:23], v[86:87], v[24:25], v[22:23]
	v_add_u32_e32 v103, s7, v102
	v_mov_b32_e32 v98, s7
	v_pk_fma_f32 v[24:25], v[88:89], v[38:39], v[34:35]
	v_pk_fma_f32 v[18:19], v[88:89], v[18:19], v[22:23]
	ds_read_b32 v0, v103 offset:2848
	ds_read_b64 v[98:99], v98 offset:3104
	v_pk_fma_f32 v[22:23], v[90:91], v[40:41], v[24:25]
	v_pk_fma_f32 v[20:21], v[90:91], v[20:21], v[18:19]
	v_add_f32_e32 v18, v22, v23
	v_add_f32_e32 v19, v20, v21
	s_nop 0
	v_add_f32_dpp v18, v18, v18 quad_perm:[1,0,3,2] row_mask:0xf bank_mask:0xf bound_ctrl:1
	v_add_f32_dpp v19, v19, v19 quad_perm:[1,0,3,2] row_mask:0xf bank_mask:0xf bound_ctrl:1
	s_nop 0
	v_add_f32_dpp v18, v18, v18 quad_perm:[2,3,0,1] row_mask:0xf bank_mask:0xf bound_ctrl:1
	v_add_f32_dpp v19, v19, v19 quad_perm:[2,3,0,1] row_mask:0xf bank_mask:0xf bound_ctrl:1
	s_nop 0
	v_add_f32_dpp v18, v18, v18 row_half_mirror row_mask:0xf bank_mask:0xf bound_ctrl:1
	v_mov_b32_e32 v22, v97
	v_mov_b32_e32 v23, v18
	v_pk_mul_f32 v[22:23], v[22:23], v[94:95]
	v_add_f32_dpp v19, v19, v19 row_half_mirror row_mask:0xf bank_mask:0xf bound_ctrl:1
	v_add_f32_e32 v19, v23, v19
	v_add_f32_e32 v19, v22, v19
	s_ashr_i32 s47, s46, 31
	v_bfe_u32 v20, v19, 16, 1
	s_lshl_b64 s[20:21], s[46:47], 9
	v_add3_u32 v19, v19, v20, s28
	v_lshl_add_u64 v[20:21], v[92:93], 0, s[20:21]
	global_store_short_d16_hi v[20:21], v19, off

.LBB0_858:
	v_pk_mul_f32 v[50:51], v[50:51], v[84:85]
	v_pk_mul_f32 v[46:47], v[46:47], v[88:89]
	s_waitcnt lgkmcnt(14)
	v_pk_fma_f32 v[50:51], v[66:67], v[62:63], v[50:51] op_sel_hi:[0,1,1]
	v_pk_fma_f32 v[46:47], v[66:67], v[58:59], v[46:47] op_sel_hi:[0,1,1]
	s_waitcnt lgkmcnt(13)
	v_pk_fma_f32 v[84:85], v[0:1], v[54:55], v[50:51] op_sel_hi:[0,1,1]
	v_pk_mul_f32 v[50:51], v[52:53], v[86:87]
	v_pk_fma_f32 v[88:89], v[0:1], v[42:43], v[46:47] op_sel_hi:[0,1,1]
	v_pk_mul_f32 v[42:43], v[48:49], v[90:91]
	v_pk_fma_f32 v[50:51], v[66:67], v[64:65], v[50:51] op_sel_hi:[0,1,1]
	v_pk_fma_f32 v[42:43], v[66:67], v[60:61], v[42:43] op_sel_hi:[0,1,1]
	s_add_i32 s46, s46, s3
	s_add_i32 s10, s10, 2
	s_addk_i32 s7, 0xc40
	v_pk_fma_f32 v[86:87], v[0:1], v[56:57], v[50:51] op_sel_hi:[0,1,1]
	s_cmp_gt_u32 s10, 13
	v_pk_fma_f32 v[90:91], v[0:1], v[44:45], v[42:43] op_sel_hi:[0,1,1]
	s_cbranch_scc0 .LBB0_859

.LBB0_867:
	s_waitcnt lgkmcnt(11)
	ds_read_b128 v[22:25], v100 offset:25088
	s_waitcnt lgkmcnt(11)
	ds_read_b128 v[18:21], v100 offset:25104
	s_waitcnt lgkmcnt(11)
	ds_read_b128 v[2:5], v100 offset:25344
	s_waitcnt lgkmcnt(11)
	ds_read_b128 v[6:9], v100 offset:25360
	s_waitcnt lgkmcnt(11)
	ds_read_b128 v[10:13], v100 offset:25600
	s_waitcnt lgkmcnt(11)
	ds_read_b128 v[14:17], v100 offset:25616
	s_waitcnt lgkmcnt(11)
	ds_read_b128 v[34:37], v100 offset:25856
	s_waitcnt lgkmcnt(11)
	ds_read_b128 v[38:41], v100 offset:25872
	s_waitcnt lgkmcnt(11)
	ds_read_b128 v[26:29], v100 offset:26112
	s_waitcnt lgkmcnt(11)
	ds_read_b128 v[30:33], v100 offset:26128
	s_waitcnt lgkmcnt(11)
	ds_read_b32 v94, v101 offset:26368
	s_waitcnt lgkmcnt(11)
	ds_read_b64 v[96:97], v1 offset:26624
	s_ashr_i32 s19, s18, 31
	s_lshl_b64 s[6:7], s[18:19], 9
	v_lshl_add_u64 v[92:93], v[82:83], 0, s[6:7]
	s_mov_b32 s6, 0
	s_mov_b32 s7, -2
	s_mov_b32 s18, 0
	v_readlane_b32 s2, v254, 61
	v_readlane_b32 s3, v254, 62
	s_branch .LBB0_869
.LBB0_869:
	s_waitcnt lgkmcnt(0)
	v_mov_b32_e32 v95, v96
	v_add_u32_e32 v96, s6, v100
	ds_read_b128 v[70:73], v96 offset:26656
	ds_read_b128 v[66:69], v96 offset:26672
	ds_read_b128 v[50:53], v96 offset:26912
	ds_read_b128 v[46:49], v96 offset:26928
	ds_read_b128 v[54:57], v96 offset:27168
	ds_read_b128 v[42:45], v96 offset:27184
	ds_read_b128 v[78:81], v96 offset:27424
	ds_read_b128 v[74:77], v96 offset:27440
	ds_read_b128 v[62:65], v96 offset:27680
	ds_read_b128 v[58:61], v96 offset:27696
	v_pk_fma_f32 v[34:35], v[84:85], v[34:35], 0 op_sel_hi:[1,1,0]
	v_pk_fma_f32 v[22:23], v[84:85], v[22:23], 0 op_sel_hi:[1,1,0]
	v_pk_fma_f32 v[34:35], v[86:87], v[36:37], v[34:35]
	v_pk_fma_f32 v[22:23], v[86:87], v[24:25], v[22:23]
	v_add_u32_e32 v103, s6, v102
	v_mov_b32_e32 v98, s6
	v_pk_fma_f32 v[24:25], v[88:89], v[38:39], v[34:35]
	v_pk_fma_f32 v[18:19], v[88:89], v[18:19], v[22:23]
	ds_read_b32 v0, v103 offset:27936
	ds_read_b64 v[98:99], v98 offset:28192
	v_pk_fma_f32 v[22:23], v[90:91], v[40:41], v[24:25]
	v_pk_fma_f32 v[20:21], v[90:91], v[20:21], v[18:19]
	v_add_f32_e32 v18, v22, v23
	v_add_f32_e32 v19, v20, v21
	s_nop 0
	v_add_f32_dpp v18, v18, v18 quad_perm:[1,0,3,2] row_mask:0xf bank_mask:0xf bound_ctrl:1
	v_add_f32_dpp v19, v19, v19 quad_perm:[1,0,3,2] row_mask:0xf bank_mask:0xf bound_ctrl:1
	s_nop 0
	v_add_f32_dpp v18, v18, v18 quad_perm:[2,3,0,1] row_mask:0xf bank_mask:0xf bound_ctrl:1
	v_add_f32_dpp v19, v19, v19 quad_perm:[2,3,0,1] row_mask:0xf bank_mask:0xf bound_ctrl:1
	s_nop 0
	v_add_f32_dpp v18, v18, v18 row_half_mirror row_mask:0xf bank_mask:0xf bound_ctrl:1
	v_mov_b32_e32 v22, v97
	v_mov_b32_e32 v23, v18
	v_pk_mul_f32 v[22:23], v[22:23], v[94:95]
	v_add_f32_dpp v19, v19, v19 row_half_mirror row_mask:0xf bank_mask:0xf bound_ctrl:1
	v_add_f32_e32 v19, v23, v19
	v_add_f32_e32 v19, v22, v19
	s_ashr_i32 s19, s18, 31
	v_bfe_u32 v20, v19, 16, 1
	s_lshl_b64 s[10:11], s[18:19], 9
	v_add3_u32 v19, v19, v20, s28
	v_lshl_add_u64 v[20:21], v[92:93], 0, s[10:11]
	global_store_short_d16_hi v[20:21], v19, off

.LBB0_868:
	v_pk_mul_f32 v[50:51], v[50:51], v[84:85]
	v_pk_mul_f32 v[46:47], v[46:47], v[88:89]
	s_waitcnt lgkmcnt(14)
	v_pk_fma_f32 v[50:51], v[66:67], v[62:63], v[50:51] op_sel_hi:[0,1,1]
	v_pk_fma_f32 v[46:47], v[66:67], v[58:59], v[46:47] op_sel_hi:[0,1,1]
	s_waitcnt lgkmcnt(13)
	v_pk_fma_f32 v[84:85], v[0:1], v[54:55], v[50:51] op_sel_hi:[0,1,1]
	v_pk_mul_f32 v[50:51], v[52:53], v[86:87]
	v_pk_fma_f32 v[88:89], v[0:1], v[42:43], v[46:47] op_sel_hi:[0,1,1]
	v_pk_mul_f32 v[42:43], v[48:49], v[90:91]
	v_pk_fma_f32 v[50:51], v[66:67], v[64:65], v[50:51] op_sel_hi:[0,1,1]
	v_pk_fma_f32 v[42:43], v[66:67], v[60:61], v[42:43] op_sel_hi:[0,1,1]
	s_add_i32 s18, s18, s3
	s_add_i32 s7, s7, 2
	s_addk_i32 s6, 0xc40
	v_pk_fma_f32 v[86:87], v[0:1], v[56:57], v[50:51] op_sel_hi:[0,1,1]
	s_cmp_gt_u32 s7, 13
	v_pk_fma_f32 v[90:91], v[0:1], v[44:45], v[42:43] op_sel_hi:[0,1,1]
	s_cbranch_scc0 .LBB0_869
	s_branch .LBB0_852

.LBB0_904:
	s_waitcnt lgkmcnt(9)
	ds_read_b128 v[30:33], v94
	s_waitcnt lgkmcnt(9)
	ds_read_b128 v[26:29], v94 offset:16
	s_waitcnt lgkmcnt(9)
	ds_read_b128 v[22:25], v94 offset:32
	s_waitcnt lgkmcnt(9)
	ds_read_b128 v[18:21], v94 offset:48
	s_waitcnt lgkmcnt(9)
	ds_read_b128 v[2:5], v94 offset:256
	s_waitcnt lgkmcnt(9)
	ds_read_b128 v[6:9], v94 offset:272
	s_waitcnt lgkmcnt(7)
	ds_read_b32 v73, v95 offset:512
	s_waitcnt lgkmcnt(7)
	ds_read_b128 v[34:37], v1 offset:768
	ds_read_b128 v[14:17], v94 offset:288
	ds_read_b128 v[10:13], v94 offset:304
	s_ashr_i32 s19, s18, 31
	s_lshl_b64 s[10:11], s[18:19], 9
	v_lshl_add_u64 v[92:93], v[76:77], 0, s[10:11]
	s_mov_b32 s7, 0
	s_mov_b32 s10, -2
	s_mov_b32 s18, 0
	s_branch .LBB0_906
.LBB0_906:
	s_waitcnt lgkmcnt(5)
	v_pk_fma_f32 v[100:101], v[74:75], v[2:3], 0 op_sel_hi:[1,1,0]
	s_waitcnt lgkmcnt(0)
	v_mov_b32_e32 v37, v34
	v_add_u32_e32 v34, s7, v94
	v_pk_fma_f32 v[30:31], v[74:75], v[30:31], 0 op_sel_hi:[1,1,0]
	v_pk_fma_f32 v[100:101], v[78:79], v[4:5], v[100:101]
	ds_read_b128 v[66:69], v34 offset:800
	ds_read_b128 v[62:65], v34 offset:816
	ds_read_b128 v[58:61], v34 offset:832
	ds_read_b128 v[54:57], v34 offset:848
	ds_read_b128 v[50:53], v34 offset:1056
	ds_read_b128 v[46:49], v34 offset:1072
	ds_read_b128 v[42:45], v34 offset:1088
	ds_read_b128 v[38:41], v34 offset:1104
	v_pk_fma_f32 v[30:31], v[78:79], v[32:33], v[30:31]
	v_pk_fma_f32 v[32:33], v[80:81], v[6:7], v[100:101]
	v_pk_fma_f32 v[26:27], v[80:81], v[26:27], v[30:31]
	v_pk_fma_f32 v[30:31], v[82:83], v[8:9], v[32:33]
	v_pk_fma_f32 v[26:27], v[82:83], v[28:29], v[26:27]
	s_waitcnt lgkmcnt(9)
	v_pk_fma_f32 v[28:29], v[84:85], v[14:15], v[30:31]
	v_pk_fma_f32 v[22:23], v[84:85], v[22:23], v[26:27]
	v_pk_fma_f32 v[26:27], v[86:87], v[16:17], v[28:29]
	v_pk_fma_f32 v[22:23], v[86:87], v[24:25], v[22:23]
	s_waitcnt lgkmcnt(8)
	v_pk_fma_f32 v[24:25], v[88:89], v[10:11], v[26:27]
	v_add_u32_e32 v98, s7, v97
	v_mov_b32_e32 v70, s7
	v_pk_fma_f32 v[18:19], v[88:89], v[18:19], v[22:23]
	v_pk_fma_f32 v[22:23], v[90:91], v[12:13], v[24:25]
	ds_read_b32 v0, v98
	ds_read_b96 v[70:72], v70 offset:1568
	v_pk_fma_f32 v[18:19], v[90:91], v[20:21], v[18:19]
	v_add_f32_e32 v20, v22, v23
	v_add_f32_e32 v18, v18, v19
	s_nop 0
	v_add_f32_dpp v20, v20, v20 quad_perm:[1,0,3,2] row_mask:0xf bank_mask:0xf bound_ctrl:1
	v_add_f32_dpp v19, v18, v18 quad_perm:[1,0,3,2] row_mask:0xf bank_mask:0xf bound_ctrl:1
	s_nop 0
	v_add_f32_dpp v20, v20, v20 quad_perm:[2,3,0,1] row_mask:0xf bank_mask:0xf bound_ctrl:1
	v_fma_f32 v18, -v37, v20, v73
	v_mul_f32_e32 v18, v35, v18
	v_add_f32_dpp v19, v19, v19 quad_perm:[2,3,0,1] row_mask:0xf bank_mask:0xf bound_ctrl:1
	v_mul_f32_e32 v20, v37, v19
	v_pk_fma_f32 v[20:21], v[36:37], v[18:19], v[20:21] op_sel_hi:[1,1,0]
	s_ashr_i32 s19, s18, 31
	v_bfe_u32 v19, v20, 16, 1
	s_lshl_b64 s[20:21], s[18:19], 9
	v_add3_u32 v19, v20, v19, s28
	v_lshl_add_u64 v[20:21], v[92:93], 0, s[20:21]
	global_store_short_d16_hi v[20:21], v19, off

.LBB0_905:
	v_pk_mul_f32 v[54:55], v[70:71], v[74:75] op_sel_hi:[0,1]
	v_pk_fma_f32 v[74:75], v[50:51], v[0:1], v[54:55] op_sel_hi:[1,0,1]
	v_pk_mul_f32 v[50:51], v[70:71], v[78:79] op_sel_hi:[0,1]
	v_pk_fma_f32 v[78:79], v[52:53], v[0:1], v[50:51] op_sel_hi:[1,0,1]
	v_pk_mul_f32 v[50:51], v[70:71], v[80:81] op_sel_hi:[0,1]
	v_pk_fma_f32 v[80:81], v[46:47], v[0:1], v[50:51] op_sel_hi:[1,0,1]
	v_pk_mul_f32 v[46:47], v[70:71], v[82:83] op_sel_hi:[0,1]
	v_pk_fma_f32 v[82:83], v[48:49], v[0:1], v[46:47] op_sel_hi:[1,0,1]
	v_pk_mul_f32 v[46:47], v[70:71], v[84:85] op_sel_hi:[0,1]
	v_pk_fma_f32 v[84:85], v[42:43], v[0:1], v[46:47] op_sel_hi:[1,0,1]
	v_pk_mul_f32 v[42:43], v[70:71], v[86:87] op_sel_hi:[0,1]
	v_pk_fma_f32 v[86:87], v[44:45], v[0:1], v[42:43] op_sel_hi:[1,0,1]
	v_pk_mul_f32 v[42:43], v[70:71], v[88:89] op_sel_hi:[0,1]
	v_pk_fma_f32 v[88:89], v[38:39], v[0:1], v[42:43] op_sel_hi:[1,0,1]
	v_pk_mul_f32 v[38:39], v[70:71], v[90:91] op_sel_hi:[0,1]
	s_add_i32 s18, s18, s25
	s_add_i32 s10, s10, 2
	s_addk_i32 s7, 0x640
	s_cmp_gt_u32 s10, 13
	v_pk_fma_f32 v[90:91], v[40:41], v[0:1], v[38:39] op_sel_hi:[1,0,1]
	s_cbranch_scc0 .LBB0_906

.LBB0_914:
	s_waitcnt lgkmcnt(9)
	ds_read_b128 v[30:33], v94 offset:12800
	s_waitcnt lgkmcnt(9)
	ds_read_b128 v[26:29], v94 offset:12816
	s_waitcnt lgkmcnt(9)
	ds_read_b128 v[22:25], v94 offset:12832
	s_waitcnt lgkmcnt(9)
	ds_read_b128 v[18:21], v94 offset:12848
	s_waitcnt lgkmcnt(9)
	ds_read_b128 v[2:5], v94 offset:13056
	s_waitcnt lgkmcnt(9)
	ds_read_b128 v[6:9], v94 offset:13072
	s_waitcnt lgkmcnt(7)
	ds_read_b32 v73, v95 offset:13312
	s_waitcnt lgkmcnt(7)
	ds_read_b128 v[34:37], v1 offset:13568
	ds_read_b128 v[14:17], v94 offset:13088
	ds_read_b128 v[10:13], v94 offset:13104
	s_ashr_i32 s17, s16, 31
	s_lshl_b64 s[6:7], s[16:17], 9
	v_lshl_add_u64 v[92:93], v[76:77], 0, s[6:7]
	s_mov_b32 s16, 0
	s_mov_b32 s6, -2
	s_movk_i32 s7, 0x3520
	s_branch .LBB0_916
.LBB0_916:
	s_waitcnt lgkmcnt(5)
	v_pk_fma_f32 v[100:101], v[74:75], v[2:3], 0 op_sel_hi:[1,1,0]
	s_waitcnt lgkmcnt(0)
	v_mov_b32_e32 v37, v34
	v_add_u32_e32 v34, s7, v94
	v_pk_fma_f32 v[30:31], v[74:75], v[30:31], 0 op_sel_hi:[1,1,0]
	v_pk_fma_f32 v[100:101], v[78:79], v[4:5], v[100:101]
	ds_read_b128 v[66:69], v34
	ds_read_b128 v[62:65], v34 offset:16
	ds_read_b128 v[58:61], v34 offset:32
	ds_read_b128 v[54:57], v34 offset:48
	ds_read_b128 v[50:53], v34 offset:256
	ds_read_b128 v[46:49], v34 offset:272
	ds_read_b128 v[42:45], v34 offset:288
	ds_read_b128 v[38:41], v34 offset:304
	v_pk_fma_f32 v[30:31], v[78:79], v[32:33], v[30:31]
	v_pk_fma_f32 v[32:33], v[80:81], v[6:7], v[100:101]
	v_pk_fma_f32 v[26:27], v[80:81], v[26:27], v[30:31]
	v_pk_fma_f32 v[30:31], v[82:83], v[8:9], v[32:33]
	v_pk_fma_f32 v[26:27], v[82:83], v[28:29], v[26:27]
	s_waitcnt lgkmcnt(9)
	v_pk_fma_f32 v[28:29], v[84:85], v[14:15], v[30:31]
	v_pk_fma_f32 v[22:23], v[84:85], v[22:23], v[26:27]
	v_pk_fma_f32 v[26:27], v[86:87], v[16:17], v[28:29]
	v_pk_fma_f32 v[22:23], v[86:87], v[24:25], v[22:23]
	s_waitcnt lgkmcnt(8)
	v_pk_fma_f32 v[24:25], v[88:89], v[10:11], v[26:27]
	v_add_u32_e32 v98, s7, v96
	v_mov_b32_e32 v70, s7
	v_pk_fma_f32 v[18:19], v[88:89], v[18:19], v[22:23]
	v_pk_fma_f32 v[22:23], v[90:91], v[12:13], v[24:25]
	ds_read_b32 v0, v98 offset:512
	ds_read_b96 v[70:72], v70 offset:768
	v_pk_fma_f32 v[18:19], v[90:91], v[20:21], v[18:19]
	v_add_f32_e32 v20, v22, v23
	v_add_f32_e32 v18, v18, v19
	s_nop 0
	v_add_f32_dpp v20, v20, v20 quad_perm:[1,0,3,2] row_mask:0xf bank_mask:0xf bound_ctrl:1
	v_add_f32_dpp v19, v18, v18 quad_perm:[1,0,3,2] row_mask:0xf bank_mask:0xf bound_ctrl:1
	s_nop 0
	v_add_f32_dpp v20, v20, v20 quad_perm:[2,3,0,1] row_mask:0xf bank_mask:0xf bound_ctrl:1
	v_fma_f32 v18, -v37, v20, v73
	v_mul_f32_e32 v18, v35, v18
	v_add_f32_dpp v19, v19, v19 quad_perm:[2,3,0,1] row_mask:0xf bank_mask:0xf bound_ctrl:1
	v_mul_f32_e32 v20, v37, v19
	v_pk_fma_f32 v[20:21], v[36:37], v[18:19], v[20:21] op_sel_hi:[1,1,0]
	s_ashr_i32 s17, s16, 31
	v_bfe_u32 v19, v20, 16, 1
	s_lshl_b64 s[10:11], s[16:17], 9
	v_add3_u32 v19, v20, v19, s28
	v_lshl_add_u64 v[20:21], v[92:93], 0, s[10:11]
	global_store_short_d16_hi v[20:21], v19, off

.LBB0_915:
	v_pk_mul_f32 v[54:55], v[70:71], v[74:75] op_sel_hi:[0,1]
	v_pk_fma_f32 v[74:75], v[50:51], v[0:1], v[54:55] op_sel_hi:[1,0,1]
	v_pk_mul_f32 v[50:51], v[70:71], v[78:79] op_sel_hi:[0,1]
	v_pk_fma_f32 v[78:79], v[52:53], v[0:1], v[50:51] op_sel_hi:[1,0,1]
	v_pk_mul_f32 v[50:51], v[70:71], v[80:81] op_sel_hi:[0,1]
	v_pk_fma_f32 v[80:81], v[46:47], v[0:1], v[50:51] op_sel_hi:[1,0,1]
	v_pk_mul_f32 v[46:47], v[70:71], v[82:83] op_sel_hi:[0,1]
	v_pk_fma_f32 v[82:83], v[48:49], v[0:1], v[46:47] op_sel_hi:[1,0,1]
	v_pk_mul_f32 v[46:47], v[70:71], v[84:85] op_sel_hi:[0,1]
	v_pk_fma_f32 v[84:85], v[42:43], v[0:1], v[46:47] op_sel_hi:[1,0,1]
	v_pk_mul_f32 v[42:43], v[70:71], v[86:87] op_sel_hi:[0,1]
	v_pk_fma_f32 v[86:87], v[44:45], v[0:1], v[42:43] op_sel_hi:[1,0,1]
	v_pk_mul_f32 v[42:43], v[70:71], v[88:89] op_sel_hi:[0,1]
	v_pk_fma_f32 v[88:89], v[38:39], v[0:1], v[42:43] op_sel_hi:[1,0,1]
	v_pk_mul_f32 v[38:39], v[70:71], v[90:91] op_sel_hi:[0,1]
	s_add_i32 s16, s16, s25
	s_add_i32 s6, s6, 2
	s_addk_i32 s7, 0x640
	s_cmp_gt_u32 s6, 13
	v_pk_fma_f32 v[90:91], v[40:41], v[0:1], v[38:39] op_sel_hi:[1,0,1]
	s_cbranch_scc0 .LBB0_916
	s_branch .LBB0_899
